# P0 weight re-layout without LDS: each lane converts 16 k x 4 n in registers and stores 64-byte row pieces directly
# baseline (speedup 1.0000x reference)
; #define LAS __attribute__((address_space(3)))
; __device__ __forceinline__ void p0_item(const float* W, int ldw, int col0, int k0, const float* gain, bf16_t* WT, int K, int drow0, LAS float* scr, int lane) {
;     float v[64];
;     const float* src = W + (size_t)k0 * ldw + col0 + lane;
; #pragma unroll
;     for (int i = 0; i < 64; ++i) v[i] = src[(size_t)i * ldw];
;     const int c = lane & 7;
; __global__ void __launch_bounds__(NWAVES * 64, 2) fwd_megakernel(Args args) {
;     ...
;         LAS float* scr = (LAS float*)(lds + wave * 16640);
;         constexpr int I_GU = (DM / 64) * (FF / 64), I_DN = (FF / 64) * (DM / 64), I_IN = (DM / 64) * (1024 / 64), I_SQ = (DM / 64) * (DM / 64), I_PP = (PLE / 64) * (DM / 64);
;         constexpr int NITEMS = 4 * I_GU + 2 * I_DN + 6 * I_IN + 2 * I_SQ + I_PP;
;         for (int it = gw; it < NITEMS; it += NGW) {
.LBB0_28:
	v_writelane_b32 v250, s30, 30
	s_nop 1
	v_writelane_b32 v250, s31, 31
	v_writelane_b32 v250, s27, 32
	s_or_b64 exec, exec, s[4:5]
	s_lshr_b32 s64, s3, 6
	s_lshl_b32 s1, s26, 3
	s_add_i32 s1, s1, s64
	s_add_u32 s4, s60, 0x200000
	s_addc_u32 s5, s61, 0
	v_writelane_b32 v250, s4, 34
	v_and_b32_e32 v168, 63, v166
	s_nop 0
	v_writelane_b32 v250, s5, 35
	s_add_u32 s4, s60, 0x2e00000
	s_addc_u32 s5, s61, 0
	v_writelane_b32 v250, s4, 36
	s_nop 1
	v_writelane_b32 v250, s5, 37
	s_add_u32 s4, s60, 0x4400000
	s_addc_u32 s5, s61, 0
	v_writelane_b32 v250, s4, 38
	s_nop 1
	v_writelane_b32 v250, s5, 39
	s_add_u32 s4, s60, 0x5400000
	s_addc_u32 s5, s61, 0
	v_writelane_b32 v250, s4, 40
	s_nop 1
	v_writelane_b32 v250, s5, 41
	s_add_u32 s4, s60, 0x5c00000
	s_addc_u32 s5, s61, 0
	v_writelane_b32 v250, s4, 42
	s_nop 1
	v_writelane_b32 v250, s5, 43
	s_add_u32 s4, s60, 0x6400000
	s_addc_u32 s5, s61, 0
	v_writelane_b32 v250, s4, 44
	s_nop 1
	v_writelane_b32 v250, s5, 45
	s_add_u32 s4, s60, 0x9000000
	s_addc_u32 s5, s61, 0
	v_writelane_b32 v250, s4, 46
	s_nop 1
	v_writelane_b32 v250, s5, 47
	s_add_u32 s4, s60, 0xa600000
	s_addc_u32 s5, s61, 0
	v_writelane_b32 v250, s4, 48
	s_nop 1
	v_writelane_b32 v250, s5, 49
	s_add_u32 s4, s60, 0xae00000
	s_addc_u32 s5, s61, 0
	v_writelane_b32 v250, s4, 50
	s_cmpk_gt_i32 s1, 0x567f
	s_nop 0
	v_writelane_b32 v250, s5, 51
	v_writelane_b32 v250, s1, 52
	s_cbranch_scc1 .LBB0_120
	v_lshrrev_b32_e32 v85, 4, v168
	v_and_b32_e32 v86, 15, v168
	v_lshlrev_b32_e32 v87, 4, v86
	v_lshlrev_b32_e32 v67, 5, v85
	v_lshlrev_b32_e32 v88, 4, v85
	v_lshlrev_b32_e32 v89, 2, v86
	v_readlane_b32 s55, v250, 52
	s_lshl_b32 s1, s62, 3

; #define LAS __attribute__((address_space(3)))
; __device__ __forceinline__ unsigned cvtpk(float lo, float hi) { f32x2 v = {lo, hi}; bf16x2_t b = __builtin_convertvector(v, bf16x2_t); return __builtin_bit_cast(unsigned, b); }
; __device__ __forceinline__ void p0_item(const float* W, int ldw, int col0, int k0, const float* gain, bf16_t* WT, int K, int drow0, LAS float* scr, int lane) {
;     float v[64];
;     const float* src = W + (size_t)k0 * ldw + col0 + lane;
; #pragma unroll
;     for (int i = 0; i < 64; ++i) v[i] = src[(size_t)i * ldw];
;     const int c = lane & 7;
;     f32x4 g0 = {1.f, 1.f, 1.f, 1.f}, g1 = {1.f, 1.f, 1.f, 1.f};
;     if (gain) { g0 = *(const f32x4*)(gain + k0 + 8 * c); g1 = *(const f32x4*)(gain + k0 + 8 * c + 4); }
; #pragma unroll
;     for (int i = 0; i < 64; ++i) scr[i * 65 + lane] = v[i];
;     asm volatile("s_waitcnt lgkmcnt(0)" ::: "memory");
; #pragma unroll
;     for (int j = 0; j < 8; ++j) { const int n = (lane >> 3) + 8 * j; const LAS float* s = scr + (8 * c) * 65 + n;
;         u32x4 o; o.x = cvtpk(s[0 * 65] * g0[0], s[1 * 65] * g0[1]); o.y = cvtpk(s[2 * 65] * g0[2], s[3 * 65] * g0[3]); o.z = cvtpk(s[4 * 65] * g1[0], s[5 * 65] * g1[1]); o.w = cvtpk(s[6 * 65] * g1[2], s[7 * 65] * g1[3]);
;         *(u32x4*)(WT + (size_t)(drow0 + n) * K + k0 + 8 * c) = o; }
.Lp0_item:
	s_cmp_eq_u64 s[34:35], 0
	s_cbranch_scc1 .Lp0_nogain
	s_lshl_b32 s4, s33, 2
	s_add_u32 s42, s34, s4
	s_addc_u32 s43, s35, 0
	global_load_dwordx4 v[68:71], v67, s[42:43]
	global_load_dwordx4 v[72:75], v67, s[42:43] offset:16
	global_load_dwordx4 v[76:79], v67, s[42:43] offset:128
	global_load_dwordx4 v[80:83], v67, s[42:43] offset:144
	s_branch .Lp0_rows
.Lp0_nogain:
	v_mov_b32_e32 v68, 1.0
	v_mov_b32_e32 v69, 1.0
	v_mov_b32_e32 v70, 1.0
	v_mov_b32_e32 v71, 1.0
	v_mov_b32_e32 v72, 1.0
	v_mov_b32_e32 v73, 1.0
	v_mov_b32_e32 v74, 1.0
	v_mov_b32_e32 v75, 1.0
	v_mov_b32_e32 v76, 1.0
	v_mov_b32_e32 v77, 1.0
	v_mov_b32_e32 v78, 1.0
	v_mov_b32_e32 v79, 1.0
	v_mov_b32_e32 v80, 1.0
	v_mov_b32_e32 v81, 1.0
	v_mov_b32_e32 v82, 1.0
	v_mov_b32_e32 v83, 1.0
.Lp0_rows:
	s_mul_i32 s4, s33, s30
	s_add_u32 s4, s4, s31
	s_lshl_b32 s4, s4, 2
	s_add_u32 s40, s28, s4
	s_addc_u32 s41, s29, 0
	s_lshl_b32 s5, s30, 2
	s_lshl_b32 s6, s5, 3
	v_mul_lo_u32 v66, v85, s6
	v_add_u32_e32 v66, v66, v87
	s_mul_i32 s6, s5, 25
	global_load_dwordx4 v[2:5], v66, s[40:41]
	s_add_u32 s40, s40, s5
	s_addc_u32 s41, s41, 0
	global_load_dwordx4 v[6:9], v66, s[40:41]
	s_add_u32 s40, s40, s5
	s_addc_u32 s41, s41, 0
	global_load_dwordx4 v[10:13], v66, s[40:41]
	s_add_u32 s40, s40, s5
	s_addc_u32 s41, s41, 0
	global_load_dwordx4 v[14:17], v66, s[40:41]
	s_add_u32 s40, s40, s5
	s_addc_u32 s41, s41, 0
	global_load_dwordx4 v[18:21], v66, s[40:41]
	s_add_u32 s40, s40, s5
	s_addc_u32 s41, s41, 0
	global_load_dwordx4 v[22:25], v66, s[40:41]
	s_add_u32 s40, s40, s5
	s_addc_u32 s41, s41, 0
	global_load_dwordx4 v[26:29], v66, s[40:41]
	s_add_u32 s40, s40, s5
	s_addc_u32 s41, s41, 0
	global_load_dwordx4 v[30:33], v66, s[40:41]
	s_add_u32 s40, s40, s6
	s_addc_u32 s41, s41, 0
	global_load_dwordx4 v[34:37], v66, s[40:41]
	s_add_u32 s40, s40, s5
	s_addc_u32 s41, s41, 0
	global_load_dwordx4 v[38:41], v66, s[40:41]
	s_add_u32 s40, s40, s5
	s_addc_u32 s41, s41, 0
	global_load_dwordx4 v[42:45], v66, s[40:41]
	s_add_u32 s40, s40, s5
	s_addc_u32 s41, s41, 0
	global_load_dwordx4 v[46:49], v66, s[40:41]
	s_add_u32 s40, s40, s5
	s_addc_u32 s41, s41, 0
	global_load_dwordx4 v[50:53], v66, s[40:41]
	s_add_u32 s40, s40, s5
	s_addc_u32 s41, s41, 0
	global_load_dwordx4 v[54:57], v66, s[40:41]
	s_add_u32 s40, s40, s5
	s_addc_u32 s41, s41, 0
	global_load_dwordx4 v[58:61], v66, s[40:41]
	s_add_u32 s40, s40, s5
	s_addc_u32 s41, s41, 0
	global_load_dwordx4 v[62:65], v66, s[40:41]
	s_mul_i32 s4, s39, s38
	s_add_u32 s4, s4, s33
	s_lshl_b32 s4, s4, 1
	s_add_u32 s44, s36, s4
	s_addc_u32 s45, s37, 0
	s_lshl_b32 s6, s38, 1
	v_mul_lo_u32 v84, v89, s6
	v_add_u32_e32 v84, v84, v88
	s_waitcnt vmcnt(15)
	v_pk_mul_f32 v[2:3], v[2:3], v[68:69] op_sel_hi:[1,0]
	v_pk_mul_f32 v[4:5], v[4:5], v[68:69] op_sel_hi:[1,0]
	s_waitcnt vmcnt(14)
	v_pk_mul_f32 v[6:7], v[6:7], v[68:69] op_sel:[0,1] op_sel_hi:[1,1]
	v_pk_mul_f32 v[8:9], v[8:9], v[68:69] op_sel:[0,1] op_sel_hi:[1,1]
	s_waitcnt vmcnt(13)
	v_pk_mul_f32 v[10:11], v[10:11], v[70:71] op_sel_hi:[1,0]
	v_pk_mul_f32 v[12:13], v[12:13], v[70:71] op_sel_hi:[1,0]
	s_waitcnt vmcnt(12)
	v_pk_mul_f32 v[14:15], v[14:15], v[70:71] op_sel:[0,1] op_sel_hi:[1,1]
	v_pk_mul_f32 v[16:17], v[16:17], v[70:71] op_sel:[0,1] op_sel_hi:[1,1]
	s_waitcnt vmcnt(11)
	v_pk_mul_f32 v[18:19], v[18:19], v[72:73] op_sel_hi:[1,0]
	v_pk_mul_f32 v[20:21], v[20:21], v[72:73] op_sel_hi:[1,0]
	s_waitcnt vmcnt(10)
	v_pk_mul_f32 v[22:23], v[22:23], v[72:73] op_sel:[0,1] op_sel_hi:[1,1]
	v_pk_mul_f32 v[24:25], v[24:25], v[72:73] op_sel:[0,1] op_sel_hi:[1,1]
	s_waitcnt vmcnt(9)
	v_pk_mul_f32 v[26:27], v[26:27], v[74:75] op_sel_hi:[1,0]
	v_pk_mul_f32 v[28:29], v[28:29], v[74:75] op_sel_hi:[1,0]
	s_waitcnt vmcnt(8)
	v_pk_mul_f32 v[30:31], v[30:31], v[74:75] op_sel:[0,1] op_sel_hi:[1,1]
	v_pk_mul_f32 v[32:33], v[32:33], v[74:75] op_sel:[0,1] op_sel_hi:[1,1]
	s_waitcnt vmcnt(7)
	v_pk_mul_f32 v[34:35], v[34:35], v[76:77] op_sel_hi:[1,0]
	v_pk_mul_f32 v[36:37], v[36:37], v[76:77] op_sel_hi:[1,0]
	s_waitcnt vmcnt(6)
	v_pk_mul_f32 v[38:39], v[38:39], v[76:77] op_sel:[0,1] op_sel_hi:[1,1]
	v_pk_mul_f32 v[40:41], v[40:41], v[76:77] op_sel:[0,1] op_sel_hi:[1,1]
	s_waitcnt vmcnt(5)
	v_pk_mul_f32 v[42:43], v[42:43], v[78:79] op_sel_hi:[1,0]
	v_pk_mul_f32 v[44:45], v[44:45], v[78:79] op_sel_hi:[1,0]
	s_waitcnt vmcnt(4)
	v_pk_mul_f32 v[46:47], v[46:47], v[78:79] op_sel:[0,1] op_sel_hi:[1,1]
	v_pk_mul_f32 v[48:49], v[48:49], v[78:79] op_sel:[0,1] op_sel_hi:[1,1]
	s_waitcnt vmcnt(3)
	v_pk_mul_f32 v[50:51], v[50:51], v[80:81] op_sel_hi:[1,0]
	v_pk_mul_f32 v[52:53], v[52:53], v[80:81] op_sel_hi:[1,0]
	s_waitcnt vmcnt(2)
	v_pk_mul_f32 v[54:55], v[54:55], v[80:81] op_sel:[0,1] op_sel_hi:[1,1]
	v_pk_mul_f32 v[56:57], v[56:57], v[80:81] op_sel:[0,1] op_sel_hi:[1,1]
	s_waitcnt vmcnt(1)
	v_pk_mul_f32 v[58:59], v[58:59], v[82:83] op_sel_hi:[1,0]
	v_pk_mul_f32 v[60:61], v[60:61], v[82:83] op_sel_hi:[1,0]
	s_waitcnt vmcnt(0)
	v_pk_mul_f32 v[62:63], v[62:63], v[82:83] op_sel:[0,1] op_sel_hi:[1,1]
	v_pk_mul_f32 v[64:65], v[64:65], v[82:83] op_sel:[0,1] op_sel_hi:[1,1]
	v_cvt_pk_bf16_f32 v96, v2, v6
	v_cvt_pk_bf16_f32 v97, v10, v14
	v_cvt_pk_bf16_f32 v98, v18, v22
	v_cvt_pk_bf16_f32 v99, v26, v30
	global_store_dwordx4 v84, v[96:99], s[44:45]
	v_cvt_pk_bf16_f32 v112, v34, v38
	v_cvt_pk_bf16_f32 v113, v42, v46
	v_cvt_pk_bf16_f32 v114, v50, v54
	v_cvt_pk_bf16_f32 v115, v58, v62
	global_store_dwordx4 v84, v[112:115], s[44:45] offset:64
	s_add_u32 s44, s44, s6
	s_addc_u32 s45, s45, 0
	v_cvt_pk_bf16_f32 v100, v3, v7
	v_cvt_pk_bf16_f32 v101, v11, v15
	v_cvt_pk_bf16_f32 v102, v19, v23
	v_cvt_pk_bf16_f32 v103, v27, v31
	global_store_dwordx4 v84, v[100:103], s[44:45]
	v_cvt_pk_bf16_f32 v116, v35, v39
	v_cvt_pk_bf16_f32 v117, v43, v47
	v_cvt_pk_bf16_f32 v118, v51, v55
	v_cvt_pk_bf16_f32 v119, v59, v63
	global_store_dwordx4 v84, v[116:119], s[44:45] offset:64
	s_add_u32 s44, s44, s6
	s_addc_u32 s45, s45, 0
	v_cvt_pk_bf16_f32 v104, v4, v8
	v_cvt_pk_bf16_f32 v105, v12, v16
	v_cvt_pk_bf16_f32 v106, v20, v24
	v_cvt_pk_bf16_f32 v107, v28, v32
	global_store_dwordx4 v84, v[104:107], s[44:45]
	v_cvt_pk_bf16_f32 v120, v36, v40
	v_cvt_pk_bf16_f32 v121, v44, v48
	v_cvt_pk_bf16_f32 v122, v52, v56
	v_cvt_pk_bf16_f32 v123, v60, v64
	global_store_dwordx4 v84, v[120:123], s[44:45] offset:64
	s_add_u32 s44, s44, s6
	s_addc_u32 s45, s45, 0
	v_cvt_pk_bf16_f32 v108, v5, v9
	v_cvt_pk_bf16_f32 v109, v13, v17
	v_cvt_pk_bf16_f32 v110, v21, v25
	v_cvt_pk_bf16_f32 v111, v29, v33
	global_store_dwordx4 v84, v[108:111], s[44:45]
	v_cvt_pk_bf16_f32 v124, v37, v41
	v_cvt_pk_bf16_f32 v125, v45, v49
	v_cvt_pk_bf16_f32 v126, v53, v57
	v_cvt_pk_bf16_f32 v127, v61, v65
	global_store_dwordx4 v84, v[124:127], s[44:45] offset:64
	s_add_i32 s55, s55, s1
	s_cmpk_gt_i32 s55, 0x567f
	s_cbranch_scc0 .Lp0_loop
